# 148 v_pk_mul_f32 (no modifiers) split into scalar v_mul_f32 pairs (swiglu epilogues and other VALU epilogues)
# speedup vs baseline: 1.0089x; 1.0089x over previous
; DI void norm_row(const Params& p, int layer, int which, int t, int lane) {
;   const float* g = (which ? p.norm_ffn : p.norm_attn) + layer * DM;
;   const float* xr = which ? (const float*)xrow_dst(p, t) : xrow_src(p, layer, t);
;   const float* md = p.mod + ((size_t)layer * 5 + mb_of(t)) * 6144 + (which ? 3 * 1024 : 0);
;   float4 v[4];
;   float ss = 0.f;
; #pragma unroll
;   for (int j = 0; j < 4; ++j) {
;     v[j] = *(const float4*)(xr + lane * 4 + 256 * j);
;     ss += v[j].x * v[j].x + v[j].y * v[j].y + v[j].z * v[j].z + v[j].w * v[j].w;
;   }
; #pragma unroll
;   for (int o = 32; o >= 1; o >>= 1) ss += __shfl_xor(ss, o);
;   float r = rsqrtf(ss * (1.f / 1024.f) + EPSV);
; #pragma unroll
;   for (int j = 0; j < 4; ++j) {
;     int col = lane * 4 + 256 * j;
;     float4 gg = *(const float4*)(g + col);
;     float4 sh = *(const float4*)(md + col);
;     float4 sc = *(const float4*)(md + 1024 + col);
;     float o0 = v[j].x * r * gg.x * (1.f + sc.x) + sh.x;
;     float o1 = v[j].y * r * gg.y * (1.f + sc.y) + sh.y;
;     float o2 = v[j].z * r * gg.z * (1.f + sc.z) + sh.z;
;     float o3 = v[j].w * r * gg.w * (1.f + sc.w) + sh.w;
;     *(uint2*)(p.H + (size_t)t * LDK + col) = make_uint2(pack_bf16(o0, o1), pack_bf16(o2, o3));
;   }
; DI void norm_static(const Params& p, int layer, int which, int row0, int row1) {
;     ...
;   for (int t = row0 + blockIdx.x * 8 + wid; t < row1; t += gridDim.x * 8) norm_row(p, layer, which, t, lane);
.LBB0_87:
	v_cmp_lt_i32_e32 vcc, v24, v23
	v_add_u32_e32 v36, 0x4000, v21
	v_mov_b64_e32 v[32:33], v[8:9]
	v_cndmask_b32_e32 v31, v22, v24, vcc
	v_cmp_lt_i32_e32 vcc, v25, v23
	v_mov_b64_e32 v[34:35], v[12:13]
	v_mov_b64_e32 v[38:39], v[6:7]
	v_cndmask_b32_e32 v42, v22, v25, vcc
	v_cmp_lt_i32_e32 vcc, v26, v23
	v_mov_b64_e32 v[40:41], v[10:11]
	v_ashrrev_i32_e32 v37, 31, v36
	v_cndmask_b32_e32 v43, v22, v26, vcc
	v_cmp_lt_i32_e32 vcc, v27, v23
	v_min_i32_e32 v47, 0x4000, v36
	v_lshlrev_b32_e32 v84, 2, v42
	v_cndmask_b32_e32 v44, v22, v27, vcc
	v_cmp_lt_i32_e32 vcc, v28, v23
	v_lshlrev_b32_e32 v85, 2, v43
	v_lshlrev_b32_e32 v86, 2, v44
	v_cndmask_b32_e32 v45, v22, v28, vcc
	v_cmp_lt_i32_e32 vcc, v29, v23
	v_ashrrev_i32_e32 v44, 12, v47
	v_lshlrev_b32_e32 v87, 2, v45
	v_cndmask_b32_e32 v46, v22, v29, vcc
	v_cmp_gt_i32_e32 vcc, s6, v36
	v_lshlrev_b32_e32 v88, 2, v46
	global_load_dwordx4 v[32:35], v[2:3], off
	v_cndmask_b32_e32 v43, 0, v37, vcc
	v_cndmask_b32_e32 v42, v21, v36, vcc
	v_cndmask_b32_e32 v39, v41, v39, vcc
	v_cndmask_b32_e32 v38, v40, v38, vcc
	v_lshlrev_b64 v[36:37], 11, v[36:37]
	v_lshlrev_b64 v[40:41], 12, v[42:43]
	v_mul_hi_i32_i24_e32 v43, 0x6000, v44
	v_mul_i32_i24_e32 v42, 0x6000, v44
	v_lshl_add_u64 v[60:61], v[4:5], 0, v[36:37]
	v_lshl_add_u64 v[36:37], v[38:39], 0, v[40:41]
	v_lshl_add_u64 v[38:39], s[62:63], 0, v[42:43]
	v_lshl_add_u64 v[48:49], v[36:37], 0, v[0:1]
	v_lshl_add_u64 v[62:63], v[38:39], 0, s[4:5]
	v_lshl_add_u64 v[64:65], v[38:39], 0, v[0:1]
	global_load_dwordx4 v[36:39], v[48:49], off
	global_load_dwordx4 v[40:43], v[48:49], off offset:1024
	global_load_dwordx4 v[44:47], v[48:49], off offset:2048
	s_nop 0
	global_load_dwordx4 v[48:51], v[48:49], off offset:3072
	v_lshl_add_u64 v[56:57], v[62:63], 0, v[0:1]
	global_load_dwordx4 v[52:55], v[64:65], off
	s_nop 0
	global_load_dwordx4 v[56:59], v[56:57], off
	v_lshlrev_b32_e32 v31, 2, v31
	v_lshl_add_u64 v[66:67], v[62:63], 0, v[14:15]
	v_add_u32_e32 v21, s7, v21
	s_waitcnt vmcnt(0) lgkmcnt(0)
	v_mov_b32_e32 v74, v37
	v_mov_b32_e32 v75, v41
	v_mov_b32_e32 v72, v36
	v_mov_b32_e32 v73, v40
	v_mov_b32_e32 v82, v45
	v_mov_b32_e32 v83, v49
	v_mul_f32_e32 v74, v74, v74
	v_mul_f32_e32 v75, v75, v75
	v_mov_b32_e32 v68, v38
	v_mov_b32_e32 v69, v42
	v_mov_b32_e32 v80, v44
	v_mov_b32_e32 v81, v48
	v_mul_f32_e32 v82, v82, v82
	v_mul_f32_e32 v83, v83, v83
	v_pk_fma_f32 v[72:73], v[72:73], v[72:73], v[74:75]
	v_mov_b32_e32 v70, v39
	v_mov_b32_e32 v71, v43
	v_mov_b32_e32 v76, v46
	v_mov_b32_e32 v77, v50
	v_pk_fma_f32 v[74:75], v[80:81], v[80:81], v[82:83]
	v_pk_fma_f32 v[68:69], v[68:69], v[68:69], v[72:73]
	v_mov_b32_e32 v78, v47
	v_mov_b32_e32 v79, v51
	v_pk_fma_f32 v[72:73], v[76:77], v[76:77], v[74:75]
	v_pk_fma_f32 v[68:69], v[70:71], v[70:71], v[68:69]
	v_pk_fma_f32 v[70:71], v[78:79], v[78:79], v[72:73]
	v_add_f32_e32 v68, v68, v69
	v_add_f32_e32 v68, v68, v70
	v_add_f32_e32 v68, v68, v71
	ds_bpermute_b32 v31, v31, v68
	v_pk_add_f32 v[56:57], v[56:57], 1.0 op_sel_hi:[1,0]
	v_pk_add_f32 v[58:59], v[58:59], 1.0 op_sel_hi:[1,0]
	s_waitcnt lgkmcnt(0)
	v_add_f32_e32 v31, v68, v31
	ds_bpermute_b32 v68, v84, v31
	s_waitcnt lgkmcnt(0)
	v_add_f32_e32 v31, v31, v68
	ds_bpermute_b32 v68, v85, v31
	s_waitcnt lgkmcnt(0)
	v_add_f32_e32 v31, v31, v68
	ds_bpermute_b32 v68, v86, v31
	s_waitcnt lgkmcnt(0)
	v_add_f32_e32 v31, v31, v68
	ds_bpermute_b32 v68, v87, v31
	s_waitcnt lgkmcnt(0)
	v_add_f32_e32 v31, v31, v68
	ds_bpermute_b32 v68, v88, v31
	s_waitcnt lgkmcnt(0)
	v_add_f32_e32 v31, v31, v68
	v_fmamk_f32 v31, v31, 0x3a800000, v30
	v_mul_f32_e32 v68, 0x4b800000, v31
	v_cmp_gt_f32_e32 vcc, s8, v31
	s_nop 1
	v_cndmask_b32_e32 v31, v31, v68, vcc
	v_rsq_f32_e32 v31, v31
	s_nop 0
	v_mul_f32_e32 v68, 0x45800000, v31
	v_cndmask_b32_e32 v68, v31, v68, vcc
	v_pk_mul_f32 v[36:37], v[36:37], v[68:69] op_sel_hi:[1,0]
	v_pk_mul_f32 v[38:39], v[38:39], v[68:69] op_sel_hi:[1,0]
	v_mul_f32_e32 v32, v32, v36
	v_mul_f32_e32 v33, v33, v37
	v_mul_f32_e32 v34, v34, v38
	v_mul_f32_e32 v35, v35, v39
	v_pk_fma_f32 v[32:33], v[56:57], v[32:33], v[52:53]
	v_pk_fma_f32 v[34:35], v[34:35], v[58:59], v[54:55]
	v_cvt_pk_bf16_f32 v32, v32, v33
	v_cvt_pk_bf16_f32 v33, v34, v35
	global_store_dwordx2 v[60:61], v[32:33], off
	global_load_dwordx4 v[32:35], v[2:3], off offset:1024
	s_nop 0
	global_load_dwordx4 v[36:39], v[66:67], off
	global_load_dwordx4 v[52:55], v[64:65], off offset:1024
	v_pk_mul_f32 v[40:41], v[40:41], v[68:69] op_sel_hi:[1,0]
	v_pk_mul_f32 v[42:43], v[42:43], v[68:69] op_sel_hi:[1,0]
	v_lshl_add_u64 v[56:57], v[62:63], 0, v[16:17]
	v_pk_mul_f32 v[44:45], v[44:45], v[68:69] op_sel_hi:[1,0]
	v_pk_mul_f32 v[46:47], v[46:47], v[68:69] op_sel_hi:[1,0]
	v_add_u32_e32 v31, 0x4000, v21
	v_cmp_lt_i32_e32 vcc, s9, v31
	s_or_b64 s[2:3], vcc, s[2:3]
	s_waitcnt vmcnt(2)
	v_mul_f32_e32 v32, v40, v32
	v_mul_f32_e32 v33, v41, v33
	s_waitcnt vmcnt(1)
	v_pk_add_f32 v[36:37], v[36:37], 1.0 op_sel_hi:[1,0]
	v_mul_f32_e32 v34, v42, v34
	v_mul_f32_e32 v35, v43, v35
	v_pk_add_f32 v[38:39], v[38:39], 1.0 op_sel_hi:[1,0]
	s_waitcnt vmcnt(0)
	v_pk_fma_f32 v[32:33], v[32:33], v[36:37], v[52:53]
	v_pk_fma_f32 v[34:35], v[34:35], v[38:39], v[54:55]
	v_cvt_pk_bf16_f32 v32, v32, v33
	v_cvt_pk_bf16_f32 v33, v34, v35
	global_store_dwordx2 v[60:61], v[32:33], off offset:512
	global_load_dwordx4 v[32:35], v[2:3], off offset:2048
	s_nop 0
	global_load_dwordx4 v[36:39], v[56:57], off
	global_load_dwordx4 v[40:43], v[64:65], off offset:2048
	v_lshl_add_u64 v[52:53], v[62:63], 0, v[18:19]
	s_waitcnt vmcnt(2)
	v_mul_f32_e32 v32, v44, v32
	v_mul_f32_e32 v33, v45, v33
	s_waitcnt vmcnt(1)
	v_pk_add_f32 v[36:37], v[36:37], 1.0 op_sel_hi:[1,0]
	v_mul_f32_e32 v34, v46, v34
	v_mul_f32_e32 v35, v47, v35
	v_pk_add_f32 v[38:39], v[38:39], 1.0 op_sel_hi:[1,0]
	s_waitcnt vmcnt(0)
	v_pk_fma_f32 v[32:33], v[32:33], v[36:37], v[40:41]
	v_pk_fma_f32 v[34:35], v[34:35], v[38:39], v[42:43]
	v_cvt_pk_bf16_f32 v32, v32, v33
	v_cvt_pk_bf16_f32 v33, v34, v35
	global_store_dwordx2 v[60:61], v[32:33], off offset:1024
	global_load_dwordx4 v[32:35], v[2:3], off offset:3072
	s_nop 0
	global_load_dwordx4 v[36:39], v[52:53], off
	global_load_dwordx4 v[40:43], v[64:65], off offset:3072
	v_pk_mul_f32 v[44:45], v[48:49], v[68:69] op_sel_hi:[1,0]
	v_pk_mul_f32 v[46:47], v[50:51], v[68:69] op_sel_hi:[1,0]
	s_waitcnt vmcnt(2)
	v_mul_f32_e32 v32, v44, v32
	v_mul_f32_e32 v33, v45, v33
	s_waitcnt vmcnt(1)
	v_pk_add_f32 v[36:37], v[36:37], 1.0 op_sel_hi:[1,0]
	v_mul_f32_e32 v34, v46, v34
	v_mul_f32_e32 v35, v47, v35
	v_pk_add_f32 v[38:39], v[38:39], 1.0 op_sel_hi:[1,0]
	s_waitcnt vmcnt(0)
	v_pk_fma_f32 v[32:33], v[32:33], v[36:37], v[40:41]
	v_pk_fma_f32 v[34:35], v[34:35], v[38:39], v[42:43]
	v_cvt_pk_bf16_f32 v32, v32, v33
	v_cvt_pk_bf16_f32 v33, v34, v35
	global_store_dwordx2 v[60:61], v[32:33], off offset:1536
	s_andn2_b64 exec, exec, s[2:3]
	s_cbranch_execnz .LBB0_87

; DI void norm_row(const Params& p, int layer, int which, int t, int lane) {
;   const float* g = (which ? p.norm_ffn : p.norm_attn) + layer * DM;
;   const float* xr = which ? (const float*)xrow_dst(p, t) : xrow_src(p, layer, t);
;   const float* md = p.mod + ((size_t)layer * 5 + mb_of(t)) * 6144 + (which ? 3 * 1024 : 0);
;   float4 v[4];
;   float ss = 0.f;
; #pragma unroll
;   for (int j = 0; j < 4; ++j) {
;     v[j] = *(const float4*)(xr + lane * 4 + 256 * j);
;     ss += v[j].x * v[j].x + v[j].y * v[j].y + v[j].z * v[j].z + v[j].w * v[j].w;
;   }
; #pragma unroll
;   for (int o = 32; o >= 1; o >>= 1) ss += __shfl_xor(ss, o);
;   float r = rsqrtf(ss * (1.f / 1024.f) + EPSV);
; DI void norm_static(const Params& p, int layer, int which, int row0, int row1) {
;     ...
;   for (int t = row0 + blockIdx.x * 8 + wid; t < row1; t += gridDim.x * 8) norm_row(p, layer, which, t, lane);
.LBB0_143:
	v_add_u32_e32 v2, 0x4000, v50
	v_mov_b64_e32 v[4:5], s[36:37]
	v_mov_b64_e32 v[6:7], s[76:77]
	v_mov_b64_e32 v[8:9], s[40:41]
	v_mov_b64_e32 v[10:11], s[64:65]
	v_cmp_gt_i32_e32 vcc, s13, v2
	v_ashrrev_i32_e32 v3, 31, v2
	v_cndmask_b32_e64 v8, v10, v8, s[4:5]
	v_cndmask_b32_e64 v9, v11, v9, s[4:5]
	v_cndmask_b32_e64 v6, v6, v4, s[4:5]
	v_cndmask_b32_e64 v7, v7, v5, s[4:5]
	v_cndmask_b32_e32 v5, 0, v3, vcc
	v_cndmask_b32_e32 v4, v50, v2, vcc
	v_cndmask_b32_e32 v7, v9, v7, vcc
	v_cndmask_b32_e32 v6, v8, v6, vcc
	v_lshlrev_b64 v[4:5], 12, v[4:5]
	v_lshl_add_u64 v[4:5], v[6:7], 0, v[4:5]
	v_lshl_add_u64 v[14:15], v[4:5], 0, v[0:1]
	v_and_b32_e32 v4, 64, v211
	v_add_u32_e32 v4, 64, v4
	v_xor_b32_e32 v5, 32, v211
	v_cmp_lt_i32_e32 vcc, v5, v4
	v_min_i32_e32 v6, 0x4000, v2
	v_ashrrev_i32_e32 v6, 12, v6
	v_cndmask_b32_e32 v5, v211, v5, vcc
	v_lshlrev_b32_e32 v51, 2, v5
	v_xor_b32_e32 v5, 16, v211
	v_cmp_lt_i32_e32 vcc, v5, v4
	v_add_u32_e32 v6, s12, v6
	v_mul_hi_i32_i24_e32 v7, 0x6000, v6
	v_cndmask_b32_e32 v5, v211, v5, vcc
	v_lshlrev_b32_e32 v52, 2, v5
	v_xor_b32_e32 v5, 8, v211
	v_cmp_lt_i32_e32 vcc, v5, v4
	v_mul_i32_i24_e32 v6, 0x6000, v6
	v_lshl_add_u64 v[6:7], s[62:63], 0, v[6:7]
	v_cndmask_b32_e32 v5, v211, v5, vcc
	v_lshlrev_b32_e32 v53, 2, v5
	v_xor_b32_e32 v5, 4, v211
	v_cmp_lt_i32_e32 vcc, v5, v4
	v_lshl_add_u64 v[16:17], v[6:7], 0, s[18:19]
	v_lshl_add_u64 v[18:19], v[16:17], 0, v[0:1]
	v_cndmask_b32_e32 v5, v211, v5, vcc
	v_lshlrev_b32_e32 v64, 2, v5
	v_xor_b32_e32 v5, 2, v211
	v_cmp_lt_i32_e32 vcc, v5, v4
	v_lshlrev_b64 v[22:23], 11, v[2:3]
	v_lshl_add_u64 v[38:39], v[6:7], 0, v[0:1]
	v_cndmask_b32_e32 v5, v211, v5, vcc
	v_lshlrev_b32_e32 v65, 2, v5
	v_xor_b32_e32 v5, 1, v211
	v_cmp_lt_i32_e32 vcc, v5, v4
	v_lshl_add_u64 v[36:37], v[28:29], 0, v[22:23]
	v_mov_b32_e32 v31, v1
	v_cndmask_b32_e32 v4, v211, v5, vcc
	s_waitcnt vmcnt(0)
	v_lshlrev_b32_e32 v66, 2, v4
	global_load_dwordx4 v[10:13], v[14:15], off
	global_load_dwordx4 v[6:9], v[26:27], off
	global_load_dwordx4 v[2:5], v[38:39], off
	s_nop 0
	global_load_dwordx4 v[18:21], v[18:19], off
	v_mov_b32_e32 v33, v1
	v_mov_b32_e32 v35, v1
	v_lshl_add_u64 v[44:45], v[16:17], 0, v[30:31]
	v_add_u32_e32 v50, s14, v50
	s_waitcnt vmcnt(0) lgkmcnt(0)
	v_mov_b32_e32 v48, v11
	v_mov_b32_e32 v46, v10
	v_mov_b32_e32 v22, v12
	v_pk_add_f32 v[42:43], v[18:19], 1.0 op_sel_hi:[1,0]
	v_pk_add_f32 v[40:41], v[20:21], 1.0 op_sel_hi:[1,0]
	global_load_dwordx4 v[18:21], v[14:15], off offset:1024
	v_mov_b32_e32 v24, v13
	s_waitcnt vmcnt(0) lgkmcnt(0)
	v_mov_b32_e32 v49, v19
	v_mov_b32_e32 v47, v18
	v_mul_f32_e32 v48, v48, v48
	v_mul_f32_e32 v49, v49, v49
	v_mov_b32_e32 v23, v20
	v_pk_fma_f32 v[46:47], v[46:47], v[46:47], v[48:49]
	v_mov_b32_e32 v25, v21
	v_pk_fma_f32 v[22:23], v[22:23], v[22:23], v[46:47]
	v_lshl_add_u64 v[46:47], v[16:17], 0, v[32:33]
	v_pk_fma_f32 v[54:55], v[24:25], v[24:25], v[22:23]
	global_load_dwordx4 v[22:25], v[14:15], off offset:2048
	v_lshl_add_u64 v[48:49], v[16:17], 0, v[34:35]
	global_load_dwordx4 v[14:17], v[14:15], off offset:3072
	v_add_f32_e32 v31, v54, v55
	s_waitcnt vmcnt(0) lgkmcnt(0)
	v_mov_b32_e32 v62, v23
	v_mov_b32_e32 v60, v22
	v_mov_b32_e32 v63, v15
	v_mov_b32_e32 v61, v14
	v_mul_f32_e32 v62, v62, v62
	v_mul_f32_e32 v63, v63, v63
	v_mov_b32_e32 v56, v24
	v_mov_b32_e32 v57, v16
	v_pk_fma_f32 v[60:61], v[60:61], v[60:61], v[62:63]
	v_mov_b32_e32 v58, v25
	v_mov_b32_e32 v59, v17
	v_pk_fma_f32 v[56:57], v[56:57], v[56:57], v[60:61]
	s_nop 0
	v_pk_fma_f32 v[56:57], v[58:59], v[58:59], v[56:57]
	s_nop 0
	v_add_f32_e32 v31, v31, v56
	v_add_f32_e32 v31, v31, v57
	ds_bpermute_b32 v33, v51, v31
	s_waitcnt lgkmcnt(0)
; DI void norm_row(const Params& p, int layer, int which, int t, int lane) {
;     ...
;   for (int o = 32; o >= 1; o >>= 1) ss += __shfl_xor(ss, o);
;   float r = rsqrtf(ss * (1.f / 1024.f) + EPSV);
; #pragma unroll
;   for (int j = 0; j < 4; ++j) {
;     int col = lane * 4 + 256 * j;
;     float4 gg = *(const float4*)(g + col);
;     float4 sh = *(const float4*)(md + col);
;     float4 sc = *(const float4*)(md + 1024 + col);
;     float o0 = v[j].x * r * gg.x * (1.f + sc.x) + sh.x;
;     float o1 = v[j].y * r * gg.y * (1.f + sc.y) + sh.y;
;     float o2 = v[j].z * r * gg.z * (1.f + sc.z) + sh.z;
;     float o3 = v[j].w * r * gg.w * (1.f + sc.w) + sh.w;
;     *(uint2*)(p.H + (size_t)t * LDK + col) = make_uint2(pack_bf16(o0, o1), pack_bf16(o2, o3));
;   }
	v_add_f32_e32 v31, v31, v33
	ds_bpermute_b32 v33, v52, v31
	s_waitcnt lgkmcnt(0)
	v_add_f32_e32 v31, v31, v33
	ds_bpermute_b32 v33, v53, v31
	s_waitcnt lgkmcnt(0)
	v_add_f32_e32 v31, v31, v33
	ds_bpermute_b32 v33, v64, v31
	s_waitcnt lgkmcnt(0)
	v_add_f32_e32 v31, v31, v33
	ds_bpermute_b32 v33, v65, v31
	s_waitcnt lgkmcnt(0)
	v_add_f32_e32 v31, v31, v33
	ds_bpermute_b32 v33, v66, v31
	s_waitcnt lgkmcnt(0)
	v_add_f32_e32 v31, v31, v33
	v_fmamk_f32 v31, v31, 0x3a800000, v210
	v_cmp_gt_f32_e32 vcc, s15, v31
	v_mul_f32_e32 v33, 0x4b800000, v31
	s_nop 0
	v_cndmask_b32_e32 v31, v31, v33, vcc
	v_rsq_f32_e32 v31, v31
	s_nop 0
	v_mul_f32_e32 v33, 0x45800000, v31
	v_cndmask_b32_e32 v52, v31, v33, vcc
	v_pk_mul_f32 v[10:11], v[10:11], v[52:53] op_sel_hi:[1,0]
	v_pk_mul_f32 v[18:19], v[18:19], v[52:53] op_sel_hi:[1,0]
	v_mul_f32_e32 v6, v6, v10
	v_mul_f32_e32 v7, v7, v11
	v_pk_mul_f32 v[14:15], v[14:15], v[52:53] op_sel_hi:[1,0]
	v_pk_fma_f32 v[2:3], v[42:43], v[6:7], v[2:3]
	v_pk_mul_f32 v[6:7], v[12:13], v[52:53] op_sel_hi:[1,0]
	v_cvt_pk_bf16_f32 v2, v2, v3
	v_mul_f32_e32 v6, v8, v6
	v_mul_f32_e32 v7, v9, v7
	s_nop 0
	v_pk_fma_f32 v[4:5], v[6:7], v[40:41], v[4:5]
	s_nop 0
	v_cvt_pk_bf16_f32 v3, v4, v5
	global_store_dwordx2 v[36:37], v[2:3], off
	global_load_dwordx4 v[2:5], v[26:27], off offset:1024
	s_nop 0
	global_load_dwordx4 v[6:9], v[38:39], off offset:1024
	global_load_dwordx4 v[10:13], v[44:45], off
	s_waitcnt vmcnt(2)
	v_mul_f32_e32 v2, v18, v2
	v_mul_f32_e32 v3, v19, v3
	v_pk_mul_f32 v[18:19], v[22:23], v[52:53] op_sel_hi:[1,0]
	s_waitcnt vmcnt(0)
	v_pk_add_f32 v[10:11], v[10:11], 1.0 op_sel_hi:[1,0]
	s_nop 0
	v_pk_fma_f32 v[2:3], v[2:3], v[10:11], v[6:7]
	v_pk_mul_f32 v[6:7], v[20:21], v[52:53] op_sel_hi:[1,0]
	v_cvt_pk_bf16_f32 v2, v2, v3
	v_mul_f32_e32 v4, v6, v4
	v_mul_f32_e32 v5, v7, v5
	v_pk_add_f32 v[6:7], v[12:13], 1.0 op_sel_hi:[1,0]
	s_nop 0
	v_pk_fma_f32 v[4:5], v[4:5], v[6:7], v[8:9]
	s_nop 0
	v_cvt_pk_bf16_f32 v3, v4, v5
	global_store_dwordx2 v[36:37], v[2:3], off offset:512
	global_load_dwordx4 v[2:5], v[26:27], off offset:2048
	s_nop 0
	global_load_dwordx4 v[6:9], v[38:39], off offset:2048
	global_load_dwordx4 v[10:13], v[46:47], off
	s_waitcnt vmcnt(2)
	v_mul_f32_e32 v2, v18, v2
	v_mul_f32_e32 v3, v19, v3
	s_waitcnt vmcnt(0)
	v_pk_add_f32 v[10:11], v[10:11], 1.0 op_sel_hi:[1,0]
	s_nop 0
	v_pk_fma_f32 v[2:3], v[2:3], v[10:11], v[6:7]
	v_pk_mul_f32 v[6:7], v[24:25], v[52:53] op_sel_hi:[1,0]
	v_cvt_pk_bf16_f32 v2, v2, v3
	v_mul_f32_e32 v4, v6, v4
	v_mul_f32_e32 v5, v7, v5
	v_pk_add_f32 v[6:7], v[12:13], 1.0 op_sel_hi:[1,0]
	s_nop 0
	v_pk_fma_f32 v[4:5], v[4:5], v[6:7], v[8:9]
	s_nop 0
	v_cvt_pk_bf16_f32 v3, v4, v5
	global_store_dwordx2 v[36:37], v[2:3], off offset:1024
	global_load_dwordx4 v[2:5], v[26:27], off offset:3072
	s_nop 0
	global_load_dwordx4 v[6:9], v[38:39], off offset:3072
	global_load_dwordx4 v[10:13], v[48:49], off
	s_waitcnt vmcnt(2)
	v_mul_f32_e32 v2, v14, v2
	v_mul_f32_e32 v3, v15, v3
	s_waitcnt vmcnt(0)
	v_pk_add_f32 v[10:11], v[10:11], 1.0 op_sel_hi:[1,0]
	s_nop 0
	v_pk_fma_f32 v[2:3], v[2:3], v[10:11], v[6:7]
	v_pk_mul_f32 v[6:7], v[16:17], v[52:53] op_sel_hi:[1,0]
	v_cvt_pk_bf16_f32 v2, v2, v3
	v_mul_f32_e32 v4, v6, v4
	v_mul_f32_e32 v5, v7, v5
	v_pk_add_f32 v[6:7], v[12:13], 1.0 op_sel_hi:[1,0]
	s_nop 0
	v_pk_fma_f32 v[4:5], v[4:5], v[6:7], v[8:9]
	s_nop 0
	v_cvt_pk_bf16_f32 v3, v4, v5
	global_store_dwordx2 v[36:37], v[2:3], off offset:1536
	v_add_u32_e32 v2, 0x4000, v50
	v_cmp_lt_i32_e32 vcc, s16, v2
	s_or_b64 s[2:3], vcc, s[2:3]
	s_andn2_b64 exec, exec, s[2:3]
	s_cbranch_execnz .LBB0_143

;   DI void operator()(const f32x4 (&acc)[2][2][4][2], const Unit& u, int wr, int wc, int fr, int fq) const {
;     asm volatile("" ::: "memory");
;     const int row0 = u.pm * BM + wr * 64 + fr, col0 = u.pn * HALF + wc * 32 + 8 * fq;
; #pragma unroll
;     for (int ai = 0; ai < 2; ++ai)
; #pragma unroll
;       for (int m = 0; m < 4; ++m) {
;         float a[8];
; #pragma unroll
;         for (int n = 0; n < 2; ++n)
; #pragma unroll
;           for (int e = 0; e < 4; ++e) {
;             float gte = acc[ai][0][m][n][e], up = acc[ai][1][m][n][e];
;             a[n * 4 + e] = gte * __builtin_amdgcn_rcpf(1.f + __builtin_amdgcn_exp2f(-gte * LOG2E)) * up;
;           }
;         *(uint4*)(act + (size_t)(row0 + ai * HALF + m * 16) * FFN + col0) =
;             make_uint4(pack_bf16(a[0], a[1]), pack_bf16(a[2], a[3]), pack_bf16(a[4], a[5]), pack_bf16(a[6], a[7]));
;       }
.LBB0_162:
	v_mul_f32_e32 v145, 0xbfb8aa3b, v122
	v_exp_f32_e32 v145, v145
	v_lshl_or_b32 v146, s47, 7, v142
	v_lshl_add_u32 v144, s48, 8, v140
	v_ashrrev_i32_e32 v147, 31, v146
	v_add_f32_e32 v145, 1.0, v145
	v_rcp_f32_e32 v148, v145
	v_mul_f32_e32 v145, 0xbfb8aa3b, v123
	v_exp_f32_e32 v145, v145
	s_movk_i32 s24, 0x1600
	s_and_b64 vcc, exec, s[2:3]
	v_add_f32_e32 v145, 1.0, v145
	v_rcp_f32_e32 v149, v145
	s_mov_b32 s47, s45
	s_mov_b32 s48, s46
	s_mov_b32 s49, s44
	v_mul_f32_e32 v122, v122, v148
	v_mul_f32_e32 v123, v123, v149
	s_nop 0
	v_mul_f32_e32 v122, v126, v122
	v_mul_f32_e32 v123, v127, v123
	v_mul_f32_e32 v126, 0xbfb8aa3b, v124
	v_mul_f32_e32 v127, 0xbfb8aa3b, v125
	v_exp_f32_e32 v126, v126
	v_exp_f32_e32 v127, v127
	v_add_f32_e32 v126, 1.0, v126
	v_add_f32_e32 v127, 1.0, v127
	v_rcp_f32_e32 v126, v126
	v_rcp_f32_e32 v127, v127
	s_nop 0
	v_mul_f32_e32 v124, v124, v126
	v_mul_f32_e32 v125, v125, v127
	v_mul_f32_e32 v126, 0xbfb8aa3b, v118
	v_mul_f32_e32 v127, 0xbfb8aa3b, v119
	v_exp_f32_e32 v126, v126
	v_exp_f32_e32 v127, v127
	v_mul_f32_e32 v124, v128, v124
	v_mul_f32_e32 v125, v129, v125
	v_add_f32_e32 v126, 1.0, v126
	v_add_f32_e32 v127, 1.0, v127
	v_rcp_f32_e32 v126, v126
	v_rcp_f32_e32 v127, v127
	s_nop 0
	v_mul_f32_e32 v118, v118, v126
	v_mul_f32_e32 v119, v119, v127
	s_nop 0
	v_mul_f32_e32 v114, v114, v118
	v_mul_f32_e32 v115, v115, v119
	v_mul_f32_e32 v118, 0xbfb8aa3b, v120
	v_mul_f32_e32 v119, 0xbfb8aa3b, v121
	v_exp_f32_e32 v118, v118
	v_exp_f32_e32 v119, v119
	v_add_f32_e32 v118, 1.0, v118
	v_add_f32_e32 v119, 1.0, v119
	v_rcp_f32_e32 v118, v118
	v_rcp_f32_e32 v119, v119
	s_nop 0
	v_mul_f32_e32 v118, v120, v118
	v_mul_f32_e32 v119, v121, v119
	s_nop 0
	v_mul_f32_e32 v116, v116, v118
	v_mul_f32_e32 v117, v117, v119
	v_cvt_pk_bf16_f32 v120, v114, v115
	v_mov_b64_e32 v[114:115], s[60:61]
	v_cvt_pk_bf16_f32 v118, v122, v123
	v_cvt_pk_bf16_f32 v121, v116, v117
	v_mad_i64_i32 v[122:123], s[22:23], v144, s24, v[114:115]
	v_lshlrev_b64 v[116:117], 1, v[146:147]
	v_cvt_pk_bf16_f32 v119, v124, v125
	v_lshl_add_u64 v[122:123], v[122:123], 0, v[116:117]
	global_store_dwordx4 v[122:123], v[118:121], off
	s_nop 1
	v_mul_f32_e32 v118, 0xbfb8aa3b, v110
	v_mul_f32_e32 v119, 0xbfb8aa3b, v111
	v_exp_f32_e32 v118, v118
	v_exp_f32_e32 v119, v119
	v_add_f32_e32 v118, 1.0, v118
	v_add_f32_e32 v119, 1.0, v119
	v_rcp_f32_e32 v118, v118
	v_rcp_f32_e32 v119, v119
	s_nop 0
	v_mul_f32_e32 v110, v110, v118
	v_mul_f32_e32 v111, v111, v119
	s_nop 0
	v_mul_f32_e32 v106, v106, v110
	v_mul_f32_e32 v107, v107, v111
	v_mul_f32_e32 v110, 0xbfb8aa3b, v112
	v_mul_f32_e32 v111, 0xbfb8aa3b, v113
	v_exp_f32_e32 v110, v110
	v_exp_f32_e32 v111, v111
	v_add_f32_e32 v110, 1.0, v110
	v_add_f32_e32 v111, 1.0, v111
	v_rcp_f32_e32 v110, v110
	v_rcp_f32_e32 v111, v111
	s_nop 0
	v_mul_f32_e32 v110, v112, v110
	v_mul_f32_e32 v111, v113, v111
	s_nop 0
	v_mul_f32_e32 v108, v108, v110
	v_mul_f32_e32 v109, v109, v111
	v_mul_f32_e32 v110, 0xbfb8aa3b, v102
	v_mul_f32_e32 v111, 0xbfb8aa3b, v103
	v_exp_f32_e32 v110, v110
	v_exp_f32_e32 v111, v111
	v_add_f32_e32 v110, 1.0, v110
	v_add_f32_e32 v111, 1.0, v111
	v_rcp_f32_e32 v110, v110
	v_rcp_f32_e32 v111, v111
	s_nop 0
	v_mul_f32_e32 v102, v102, v110
	v_mul_f32_e32 v103, v103, v111
	s_nop 0
	v_mul_f32_e32 v102, v98, v102
	v_mul_f32_e32 v103, v99, v103
	v_mul_f32_e32 v98, 0xbfb8aa3b, v104
	v_mul_f32_e32 v99, 0xbfb8aa3b, v105
	v_exp_f32_e32 v98, v98
	v_exp_f32_e32 v99, v99
	v_add_f32_e32 v98, 1.0, v98
	v_add_f32_e32 v99, 1.0, v99
	v_rcp_f32_e32 v98, v98
	v_rcp_f32_e32 v99, v99
	s_nop 0
	v_mul_f32_e32 v98, v104, v98
	v_mul_f32_e32 v99, v105, v99
	s_nop 0
	v_mul_f32_e32 v104, v100, v98
	v_mul_f32_e32 v105, v101, v99
	v_cvt_pk_bf16_f32 v100, v102, v103
	v_or_b32_e32 v102, 16, v144
	v_mad_i64_i32 v[102:103], s[22:23], v102, s24, v[114:115]
	v_cvt_pk_bf16_f32 v98, v106, v107
	v_cvt_pk_bf16_f32 v99, v108, v109
	v_cvt_pk_bf16_f32 v101, v104, v105
	v_lshl_add_u64 v[102:103], v[102:103], 0, v[116:117]
	global_store_dwordx4 v[102:103], v[98:101], off
	s_nop 1
	v_mul_f32_e32 v98, 0xbfb8aa3b, v94
	v_mul_f32_e32 v99, 0xbfb8aa3b, v95
	v_exp_f32_e32 v98, v98
	v_exp_f32_e32 v99, v99
	v_add_f32_e32 v98, 1.0, v98
	v_add_f32_e32 v99, 1.0, v99
	v_rcp_f32_e32 v98, v98
	v_rcp_f32_e32 v99, v99
	s_nop 0
	v_mul_f32_e32 v94, v94, v98
	v_mul_f32_e32 v95, v95, v99
	s_nop 0
	v_mul_f32_e32 v90, v90, v94
	v_mul_f32_e32 v91, v91, v95
	v_mul_f32_e32 v94, 0xbfb8aa3b, v96
	v_mul_f32_e32 v95, 0xbfb8aa3b, v97
	v_exp_f32_e32 v94, v94
	v_exp_f32_e32 v95, v95
	v_add_f32_e32 v94, 1.0, v94
	v_add_f32_e32 v95, 1.0, v95
	v_rcp_f32_e32 v94, v94
	v_rcp_f32_e32 v95, v95
	s_nop 0
	v_mul_f32_e32 v94, v96, v94
	v_mul_f32_e32 v95, v97, v95
	s_nop 0
	v_mul_f32_e32 v92, v92, v94
	v_mul_f32_e32 v93, v93, v95
	v_mul_f32_e32 v94, 0xbfb8aa3b, v86
	v_mul_f32_e32 v95, 0xbfb8aa3b, v87
	v_exp_f32_e32 v94, v94
	v_exp_f32_e32 v95, v95
	v_add_f32_e32 v94, 1.0, v94
	v_add_f32_e32 v95, 1.0, v95
	v_rcp_f32_e32 v94, v94
	v_rcp_f32_e32 v95, v95
	s_nop 0
	v_mul_f32_e32 v86, v86, v94
	v_mul_f32_e32 v87, v87, v95
	s_nop 0
	v_mul_f32_e32 v86, v82, v86
	v_mul_f32_e32 v87, v83, v87
	v_mul_f32_e32 v82, 0xbfb8aa3b, v88
	v_mul_f32_e32 v83, 0xbfb8aa3b, v89
	v_exp_f32_e32 v82, v82
	v_exp_f32_e32 v83, v83
	v_add_f32_e32 v82, 1.0, v82
	v_add_f32_e32 v83, 1.0, v83
	v_rcp_f32_e32 v82, v82
	v_rcp_f32_e32 v83, v83
	s_nop 0
	v_mul_f32_e32 v82, v88, v82
	v_mul_f32_e32 v83, v89, v83
	s_nop 0
	v_mul_f32_e32 v88, v84, v82
	v_mul_f32_e32 v89, v85, v83
	v_cvt_pk_bf16_f32 v84, v86, v87
	v_or_b32_e32 v86, 32, v144
	v_mad_i64_i32 v[86:87], s[22:23], v86, s24, v[114:115]
	v_cvt_pk_bf16_f32 v82, v90, v91
	v_cvt_pk_bf16_f32 v83, v92, v93
;   DI void operator()(const f32x4 (&acc)[2][2][4][2], const Unit& u, int wr, int wc, int fr, int fq) const {
;     asm volatile("" ::: "memory");
;     const int row0 = u.pm * BM + wr * 64 + fr, col0 = u.pn * HALF + wc * 32 + 8 * fq;
; #pragma unroll
;     for (int ai = 0; ai < 2; ++ai)
; #pragma unroll
;       for (int m = 0; m < 4; ++m) {
;         float a[8];
; #pragma unroll
;         for (int n = 0; n < 2; ++n)
; #pragma unroll
;           for (int e = 0; e < 4; ++e) {
;             float gte = acc[ai][0][m][n][e], up = acc[ai][1][m][n][e];
;             a[n * 4 + e] = gte * __builtin_amdgcn_rcpf(1.f + __builtin_amdgcn_exp2f(-gte * LOG2E)) * up;
;           }
;         *(uint4*)(act + (size_t)(row0 + ai * HALF + m * 16) * FFN + col0) =
;             make_uint4(pack_bf16(a[0], a[1]), pack_bf16(a[2], a[3]), pack_bf16(a[4], a[5]), pack_bf16(a[6], a[7]));
;       }
	v_cvt_pk_bf16_f32 v85, v88, v89
	v_lshl_add_u64 v[86:87], v[86:87], 0, v[116:117]
	global_store_dwordx4 v[86:87], v[82:85], off
	s_nop 1
	v_mul_f32_e32 v82, 0xbfb8aa3b, v78
	v_mul_f32_e32 v83, 0xbfb8aa3b, v79
	v_exp_f32_e32 v82, v82
	v_exp_f32_e32 v83, v83
	v_add_f32_e32 v82, 1.0, v82
	v_add_f32_e32 v83, 1.0, v83
	v_rcp_f32_e32 v82, v82
	v_rcp_f32_e32 v83, v83
	s_nop 0
	v_mul_f32_e32 v78, v78, v82
	v_mul_f32_e32 v79, v79, v83
	s_nop 0
	v_mul_f32_e32 v74, v74, v78
	v_mul_f32_e32 v75, v75, v79
	v_mul_f32_e32 v78, 0xbfb8aa3b, v80
	v_mul_f32_e32 v79, 0xbfb8aa3b, v81
	v_exp_f32_e32 v78, v78
	v_exp_f32_e32 v79, v79
	v_add_f32_e32 v78, 1.0, v78
	v_add_f32_e32 v79, 1.0, v79
	v_rcp_f32_e32 v78, v78
	v_rcp_f32_e32 v79, v79
	s_nop 0
	v_mul_f32_e32 v78, v80, v78
	v_mul_f32_e32 v79, v81, v79
	s_nop 0
	v_mul_f32_e32 v76, v76, v78
	v_mul_f32_e32 v77, v77, v79
	v_mul_f32_e32 v78, 0xbfb8aa3b, v70
	v_mul_f32_e32 v79, 0xbfb8aa3b, v71
	v_exp_f32_e32 v78, v78
	v_exp_f32_e32 v79, v79
	v_add_f32_e32 v78, 1.0, v78
	v_add_f32_e32 v79, 1.0, v79
	v_rcp_f32_e32 v78, v78
	v_rcp_f32_e32 v79, v79
	s_nop 0
	v_mul_f32_e32 v70, v70, v78
	v_mul_f32_e32 v71, v71, v79
	s_nop 0
	v_mul_f32_e32 v70, v66, v70
	v_mul_f32_e32 v71, v67, v71
	v_mul_f32_e32 v66, 0xbfb8aa3b, v72
	v_mul_f32_e32 v67, 0xbfb8aa3b, v73
	v_exp_f32_e32 v66, v66
	v_exp_f32_e32 v67, v67
	v_add_f32_e32 v66, 1.0, v66
	v_add_f32_e32 v67, 1.0, v67
	v_rcp_f32_e32 v66, v66
	v_rcp_f32_e32 v67, v67
	s_nop 0
	v_mul_f32_e32 v66, v72, v66
	v_mul_f32_e32 v67, v73, v67
	s_nop 0
	v_mul_f32_e32 v72, v68, v66
	v_mul_f32_e32 v73, v69, v67
	v_cvt_pk_bf16_f32 v68, v70, v71
	v_or_b32_e32 v70, 48, v144
	v_mad_i64_i32 v[70:71], s[22:23], v70, s24, v[114:115]
	v_cvt_pk_bf16_f32 v66, v74, v75
	v_cvt_pk_bf16_f32 v67, v76, v77
	v_cvt_pk_bf16_f32 v69, v72, v73
	v_lshl_add_u64 v[70:71], v[70:71], 0, v[116:117]
	global_store_dwordx4 v[70:71], v[66:69], off
	s_nop 1
	v_mul_f32_e32 v66, 0xbfb8aa3b, v62
	v_mul_f32_e32 v67, 0xbfb8aa3b, v63
	v_exp_f32_e32 v66, v66
	v_exp_f32_e32 v67, v67
	v_add_u32_e32 v68, 0x80, v144
	v_add_f32_e32 v66, 1.0, v66
	v_add_f32_e32 v67, 1.0, v67
	v_rcp_f32_e32 v66, v66
	v_rcp_f32_e32 v67, v67
	s_nop 0
	v_mul_f32_e32 v62, v62, v66
	v_mul_f32_e32 v63, v63, v67
	s_nop 0
	v_mul_f32_e32 v58, v58, v62
	v_mul_f32_e32 v59, v59, v63
	v_mul_f32_e32 v62, 0xbfb8aa3b, v64
	v_mul_f32_e32 v63, 0xbfb8aa3b, v65
	v_exp_f32_e32 v62, v62
	v_exp_f32_e32 v63, v63
	v_add_f32_e32 v62, 1.0, v62
	v_add_f32_e32 v63, 1.0, v63
	v_rcp_f32_e32 v62, v62
	v_rcp_f32_e32 v63, v63
	s_nop 0
	v_mul_f32_e32 v62, v64, v62
	v_mul_f32_e32 v63, v65, v63
	s_nop 0
	v_mul_f32_e32 v60, v60, v62
	v_mul_f32_e32 v61, v61, v63
	v_mul_f32_e32 v62, 0xbfb8aa3b, v54
	v_mul_f32_e32 v63, 0xbfb8aa3b, v55
	v_exp_f32_e32 v62, v62
	v_exp_f32_e32 v63, v63
	v_add_f32_e32 v62, 1.0, v62
	v_add_f32_e32 v63, 1.0, v63
	v_rcp_f32_e32 v62, v62
	v_rcp_f32_e32 v63, v63
	s_nop 0
	v_mul_f32_e32 v54, v54, v62
	v_mul_f32_e32 v55, v55, v63
	s_nop 0
	v_mul_f32_e32 v54, v50, v54
	v_mul_f32_e32 v55, v51, v55
	v_mul_f32_e32 v50, 0xbfb8aa3b, v56
	v_mul_f32_e32 v51, 0xbfb8aa3b, v57
	v_exp_f32_e32 v50, v50
	v_exp_f32_e32 v51, v51
	v_add_f32_e32 v50, 1.0, v50
	v_add_f32_e32 v51, 1.0, v51
	v_rcp_f32_e32 v50, v50
	v_rcp_f32_e32 v51, v51
	s_nop 0
	v_mul_f32_e32 v50, v56, v50
	v_mul_f32_e32 v51, v57, v51
	s_nop 0
	v_mul_f32_e32 v56, v52, v50
	v_mul_f32_e32 v57, v53, v51
	v_cvt_pk_bf16_f32 v52, v54, v55
	v_mad_i64_i32 v[54:55], s[22:23], v68, s24, v[114:115]
	v_cvt_pk_bf16_f32 v50, v58, v59
	v_cvt_pk_bf16_f32 v51, v60, v61
	v_cvt_pk_bf16_f32 v53, v56, v57
	v_lshl_add_u64 v[54:55], v[54:55], 0, v[116:117]
	global_store_dwordx4 v[54:55], v[50:53], off
	s_nop 1
	v_mul_f32_e32 v50, 0xbfb8aa3b, v46
	v_mul_f32_e32 v51, 0xbfb8aa3b, v47
	v_exp_f32_e32 v50, v50
	v_exp_f32_e32 v51, v51
	v_add_f32_e32 v50, 1.0, v50
	v_add_f32_e32 v51, 1.0, v51
	v_rcp_f32_e32 v50, v50
	v_rcp_f32_e32 v51, v51
	s_nop 0
	v_mul_f32_e32 v46, v46, v50
	v_mul_f32_e32 v47, v47, v51
	s_nop 0
	v_mul_f32_e32 v42, v42, v46
	v_mul_f32_e32 v43, v43, v47
	v_mul_f32_e32 v46, 0xbfb8aa3b, v48
	v_mul_f32_e32 v47, 0xbfb8aa3b, v49
	v_exp_f32_e32 v46, v46
	v_exp_f32_e32 v47, v47
	v_add_f32_e32 v46, 1.0, v46
	v_add_f32_e32 v47, 1.0, v47
	v_rcp_f32_e32 v46, v46
	v_rcp_f32_e32 v47, v47
	s_nop 0
	v_mul_f32_e32 v46, v48, v46
	v_mul_f32_e32 v47, v49, v47
	s_nop 0
	v_mul_f32_e32 v44, v44, v46
	v_mul_f32_e32 v45, v45, v47
	v_mul_f32_e32 v46, 0xbfb8aa3b, v38
	v_mul_f32_e32 v47, 0xbfb8aa3b, v39
	v_exp_f32_e32 v46, v46
;   DI void operator()(const f32x4 (&acc)[2][2][4][2], const Unit& u, int wr, int wc, int fr, int fq) const {
;     asm volatile("" ::: "memory");
;     const int row0 = u.pm * BM + wr * 64 + fr, col0 = u.pn * HALF + wc * 32 + 8 * fq;
; #pragma unroll
;     for (int ai = 0; ai < 2; ++ai)
; #pragma unroll
;       for (int m = 0; m < 4; ++m) {
;         float a[8];
; #pragma unroll
;         for (int n = 0; n < 2; ++n)
; #pragma unroll
;           for (int e = 0; e < 4; ++e) {
;             float gte = acc[ai][0][m][n][e], up = acc[ai][1][m][n][e];
;             a[n * 4 + e] = gte * __builtin_amdgcn_rcpf(1.f + __builtin_amdgcn_exp2f(-gte * LOG2E)) * up;
;           }
;         *(uint4*)(act + (size_t)(row0 + ai * HALF + m * 16) * FFN + col0) =
;             make_uint4(pack_bf16(a[0], a[1]), pack_bf16(a[2], a[3]), pack_bf16(a[4], a[5]), pack_bf16(a[6], a[7]));
;       }
	v_exp_f32_e32 v47, v47
	v_add_f32_e32 v46, 1.0, v46
	v_add_f32_e32 v47, 1.0, v47
	v_rcp_f32_e32 v46, v46
	v_rcp_f32_e32 v47, v47
	s_nop 0
	v_mul_f32_e32 v38, v38, v46
	v_mul_f32_e32 v39, v39, v47
	s_nop 0
	v_mul_f32_e32 v38, v34, v38
	v_mul_f32_e32 v39, v35, v39
	v_mul_f32_e32 v34, 0xbfb8aa3b, v40
	v_mul_f32_e32 v35, 0xbfb8aa3b, v41
	v_exp_f32_e32 v34, v34
	v_exp_f32_e32 v35, v35
	v_add_f32_e32 v34, 1.0, v34
	v_add_f32_e32 v35, 1.0, v35
	v_rcp_f32_e32 v34, v34
	v_rcp_f32_e32 v35, v35
	s_nop 0
	v_mul_f32_e32 v34, v40, v34
	v_mul_f32_e32 v35, v41, v35
	s_nop 0
	v_mul_f32_e32 v40, v36, v34
	v_mul_f32_e32 v41, v37, v35
	v_cvt_pk_bf16_f32 v36, v38, v39
	v_add_u32_e32 v38, 0x90, v144
	v_mad_i64_i32 v[38:39], s[22:23], v38, s24, v[114:115]
	v_cvt_pk_bf16_f32 v34, v42, v43
	v_cvt_pk_bf16_f32 v35, v44, v45
	v_cvt_pk_bf16_f32 v37, v40, v41
	v_lshl_add_u64 v[38:39], v[38:39], 0, v[116:117]
	global_store_dwordx4 v[38:39], v[34:37], off
	s_nop 1
	v_mul_f32_e32 v34, 0xbfb8aa3b, v30
	v_mul_f32_e32 v35, 0xbfb8aa3b, v31
	v_exp_f32_e32 v34, v34
	v_exp_f32_e32 v35, v35
	v_add_f32_e32 v34, 1.0, v34
	v_add_f32_e32 v35, 1.0, v35
	v_rcp_f32_e32 v34, v34
	v_rcp_f32_e32 v35, v35
	s_nop 0
	v_mul_f32_e32 v30, v30, v34
	v_mul_f32_e32 v31, v31, v35
	s_nop 0
	v_mul_f32_e32 v26, v26, v30
	v_mul_f32_e32 v27, v27, v31
	v_mul_f32_e32 v30, 0xbfb8aa3b, v32
	v_mul_f32_e32 v31, 0xbfb8aa3b, v33
	v_exp_f32_e32 v30, v30
	v_exp_f32_e32 v31, v31
	v_add_f32_e32 v30, 1.0, v30
	v_add_f32_e32 v31, 1.0, v31
	v_rcp_f32_e32 v30, v30
	v_rcp_f32_e32 v31, v31
	s_nop 0
	v_mul_f32_e32 v30, v32, v30
	v_mul_f32_e32 v31, v33, v31
	s_nop 0
	v_mul_f32_e32 v28, v28, v30
	v_mul_f32_e32 v29, v29, v31
	v_mul_f32_e32 v30, 0xbfb8aa3b, v22
	v_mul_f32_e32 v31, 0xbfb8aa3b, v23
	v_exp_f32_e32 v30, v30
	v_exp_f32_e32 v31, v31
	v_add_f32_e32 v30, 1.0, v30
	v_add_f32_e32 v31, 1.0, v31
	v_rcp_f32_e32 v30, v30
	v_rcp_f32_e32 v31, v31
	s_nop 0
	v_mul_f32_e32 v22, v22, v30
	v_mul_f32_e32 v23, v23, v31
	s_nop 0
	v_mul_f32_e32 v22, v18, v22
	v_mul_f32_e32 v23, v19, v23
	v_mul_f32_e32 v18, 0xbfb8aa3b, v24
	v_mul_f32_e32 v19, 0xbfb8aa3b, v25
	v_exp_f32_e32 v18, v18
	v_exp_f32_e32 v19, v19
	v_add_f32_e32 v18, 1.0, v18
	v_add_f32_e32 v19, 1.0, v19
	v_rcp_f32_e32 v18, v18
	v_rcp_f32_e32 v19, v19
	s_nop 0
	v_mul_f32_e32 v18, v24, v18
	v_mul_f32_e32 v19, v25, v19
	s_nop 0
	v_mul_f32_e32 v24, v20, v18
	v_mul_f32_e32 v25, v21, v19
	v_cvt_pk_bf16_f32 v20, v22, v23
	v_add_u32_e32 v22, 0xa0, v144
	v_mad_i64_i32 v[22:23], s[22:23], v22, s24, v[114:115]
	v_cvt_pk_bf16_f32 v18, v26, v27
	v_cvt_pk_bf16_f32 v19, v28, v29
	v_cvt_pk_bf16_f32 v21, v24, v25
	v_lshl_add_u64 v[22:23], v[22:23], 0, v[116:117]
	global_store_dwordx4 v[22:23], v[18:21], off
	s_nop 1
	v_mul_f32_e32 v18, 0xbfb8aa3b, v14
	v_mul_f32_e32 v19, 0xbfb8aa3b, v15
	v_exp_f32_e32 v18, v18
	v_exp_f32_e32 v19, v19
	v_add_f32_e32 v18, 1.0, v18
	v_add_f32_e32 v19, 1.0, v19
	v_rcp_f32_e32 v18, v18
	v_rcp_f32_e32 v19, v19
	s_nop 0
	v_mul_f32_e32 v14, v14, v18
	v_mul_f32_e32 v15, v15, v19
	s_nop 0
	v_mul_f32_e32 v10, v10, v14
	v_mul_f32_e32 v11, v11, v15
	v_mul_f32_e32 v14, 0xbfb8aa3b, v16
	v_mul_f32_e32 v15, 0xbfb8aa3b, v17
	v_exp_f32_e32 v14, v14
	v_exp_f32_e32 v15, v15
	v_add_f32_e32 v14, 1.0, v14
	v_add_f32_e32 v15, 1.0, v15
	v_rcp_f32_e32 v14, v14
	v_rcp_f32_e32 v15, v15
	s_nop 0
	v_mul_f32_e32 v14, v16, v14
	v_mul_f32_e32 v15, v17, v15
	s_nop 0
	v_mul_f32_e32 v12, v12, v14
	v_mul_f32_e32 v13, v13, v15
	v_mul_f32_e32 v14, 0xbfb8aa3b, v6
	v_mul_f32_e32 v15, 0xbfb8aa3b, v7
	v_exp_f32_e32 v14, v14
	v_exp_f32_e32 v15, v15
	v_add_f32_e32 v14, 1.0, v14
	v_add_f32_e32 v15, 1.0, v15
	v_rcp_f32_e32 v14, v14
	v_rcp_f32_e32 v15, v15
	s_nop 0
	v_mul_f32_e32 v6, v6, v14
	v_mul_f32_e32 v7, v7, v15
	s_nop 0
	v_mul_f32_e32 v6, v2, v6
	v_mul_f32_e32 v7, v3, v7
	v_mul_f32_e32 v2, 0xbfb8aa3b, v8
	v_mul_f32_e32 v3, 0xbfb8aa3b, v9
	v_exp_f32_e32 v2, v2
	v_exp_f32_e32 v3, v3
	v_add_f32_e32 v2, 1.0, v2
	v_add_f32_e32 v3, 1.0, v3
	v_rcp_f32_e32 v2, v2
	v_rcp_f32_e32 v3, v3
	s_nop 0
	v_mul_f32_e32 v2, v8, v2
	v_mul_f32_e32 v3, v9, v3
	s_nop 0
	v_mul_f32_e32 v8, v4, v2
	v_mul_f32_e32 v9, v5, v3
	v_cvt_pk_bf16_f32 v4, v6, v7
	v_add_u32_e32 v6, 0xb0, v144
	v_mad_i64_i32 v[6:7], s[22:23], v6, s24, v[114:115]
	v_cvt_pk_bf16_f32 v2, v10, v11
	v_cvt_pk_bf16_f32 v3, v12, v13
	v_cvt_pk_bf16_f32 v5, v8, v9
	v_lshl_add_u64 v[6:7], v[6:7], 0, v[116:117]
	s_mov_b64 s[24:25], s[20:21]
	s_mov_b64 s[22:23], s[18:19]
	global_store_dwordx4 v[6:7], v[2:5], off
	s_cbranch_vccnz .LBB0_179

;   DI void operator()(const f32x4 (&acc)[2][2][4][2], const Unit& u, int wr, int wc, int fr, int fq) const {
;     asm volatile("" ::: "memory");
;     const int row0 = u.pm * BM + wr * 64 + fr, col0 = u.pn * HALF + wc * 32 + 8 * fq;
; #pragma unroll
;     for (int ai = 0; ai < 2; ++ai)
; #pragma unroll
;       for (int m = 0; m < 4; ++m) {
;         float a[8];
; #pragma unroll
;         for (int n = 0; n < 2; ++n)
; #pragma unroll
;           for (int e = 0; e < 4; ++e) {
;             float gte = acc[ai][0][m][n][e], up = acc[ai][1][m][n][e];
;             a[n * 4 + e] = gte * __builtin_amdgcn_rcpf(1.f + __builtin_amdgcn_exp2f(-gte * LOG2E)) * up;
;           }
;         *(uint4*)(act + (size_t)(row0 + ai * HALF + m * 16) * FFN + col0) =
;             make_uint4(pack_bf16(a[0], a[1]), pack_bf16(a[2], a[3]), pack_bf16(a[4], a[5]), pack_bf16(a[6], a[7]));
;       }
.LBB0_192:
	v_mul_f32_e32 v0, 0xbfb8aa3b, v126
	v_exp_f32_e32 v130, v0
	v_mul_f32_e32 v0, 0xbfb8aa3b, v127
	v_exp_f32_e32 v131, v0
	v_readlane_b32 s0, v253, 12
	v_add_f32_e32 v130, 1.0, v130
	v_rcp_f32_e32 v130, v130
	v_add_f32_e32 v131, 1.0, v131
	v_rcp_f32_e32 v131, v131
	v_add_u32_e32 v0, s0, v141
	v_readlane_b32 s0, v253, 5
	s_movk_i32 s2, 0x1600
	v_mul_f32_e32 v126, v126, v130
	v_mul_f32_e32 v127, v127, v131
	v_mul_f32_e32 v130, 0xbfb8aa3b, v128
	v_mul_f32_e32 v131, 0xbfb8aa3b, v129
	v_exp_f32_e32 v130, v130
	v_exp_f32_e32 v131, v131
	v_mul_f32_e32 v122, v122, v126
	v_mul_f32_e32 v123, v123, v127
	v_or_b32_e32 v132, s0, v140
	v_add_f32_e32 v126, 1.0, v130
	v_add_f32_e32 v127, 1.0, v131
	v_mul_f32_e32 v130, 0xbfb8aa3b, v118
	v_mul_f32_e32 v131, 0xbfb8aa3b, v119
	v_rcp_f32_e32 v126, v126
	v_rcp_f32_e32 v127, v127
	v_exp_f32_e32 v130, v130
	v_exp_f32_e32 v131, v131
	v_readlane_b32 s0, v252, 44
	v_mul_f32_e32 v126, v128, v126
	v_mul_f32_e32 v127, v129, v127
	v_add_f32_e32 v128, 1.0, v130
	v_add_f32_e32 v129, 1.0, v131
	v_mul_f32_e32 v130, 0xbfb8aa3b, v120
	v_mul_f32_e32 v131, 0xbfb8aa3b, v121
	v_exp_f32_e32 v130, v130
	v_exp_f32_e32 v131, v131
	v_rcp_f32_e32 v128, v128
	v_rcp_f32_e32 v129, v129
	v_add_f32_e32 v130, 1.0, v130
	v_add_f32_e32 v131, 1.0, v131
	v_rcp_f32_e32 v130, v130
	v_rcp_f32_e32 v131, v131
	v_mul_f32_e32 v118, v118, v128
	v_mul_f32_e32 v119, v119, v129
	v_or_b32_e32 v132, s21, v132
	v_mul_f32_e32 v114, v114, v118
	v_mul_f32_e32 v115, v115, v119
	v_mul_f32_e32 v118, v120, v130
	v_mul_f32_e32 v119, v121, v131
	v_mul_f32_e32 v124, v124, v126
	v_mul_f32_e32 v125, v125, v127
	v_mul_f32_e32 v116, v116, v118
	v_mul_f32_e32 v117, v117, v119
	v_readlane_b32 s1, v252, 45
	v_cvt_pk_bf16_f32 v121, v116, v117
	v_mul_f32_e32 v116, 0xbfb8aa3b, v110
	v_exp_f32_e32 v116, v116
	v_mul_f32_e32 v117, 0xbfb8aa3b, v111
	v_exp_f32_e32 v117, v117
	v_ashrrev_i32_e32 v133, 31, v132
	v_add_f32_e32 v116, 1.0, v116
	v_cvt_pk_bf16_f32 v119, v124, v125
	v_cvt_pk_bf16_f32 v120, v114, v115
	v_mov_b64_e32 v[114:115], s[0:1]
	v_rcp_f32_e32 v124, v116
	v_add_f32_e32 v116, 1.0, v117
	v_cvt_pk_bf16_f32 v118, v122, v123
	v_mad_i64_i32 v[122:123], s[0:1], v0, s2, v[114:115]
	v_rcp_f32_e32 v125, v116
	v_lshlrev_b64 v[116:117], 1, v[132:133]
	v_lshl_add_u64 v[122:123], v[122:123], 0, v[116:117]
	global_store_dwordx4 v[122:123], v[118:121], off
	v_mul_f32_e32 v110, v110, v124
	v_mul_f32_e32 v111, v111, v125
	s_cmpk_lt_u32 s20, 0x100
	v_mul_f32_e32 v118, 0xbfb8aa3b, v112
	v_mul_f32_e32 v119, 0xbfb8aa3b, v113
	v_exp_f32_e32 v118, v118
	v_exp_f32_e32 v119, v119
	v_mul_f32_e32 v106, v106, v110
	v_mul_f32_e32 v107, v107, v111
	s_mov_b64 s[22:23], 0x3000
	v_add_f32_e32 v110, 1.0, v118
	v_add_f32_e32 v111, 1.0, v119
	v_mul_f32_e32 v118, 0xbfb8aa3b, v102
	v_mul_f32_e32 v119, 0xbfb8aa3b, v103
	v_rcp_f32_e32 v110, v110
	v_rcp_f32_e32 v111, v111
	v_exp_f32_e32 v118, v118
	v_exp_f32_e32 v119, v119
	v_mul_f32_e32 v110, v112, v110
	v_mul_f32_e32 v111, v113, v111
	v_add_f32_e32 v112, 1.0, v118
	v_add_f32_e32 v113, 1.0, v119
	v_mul_f32_e32 v118, 0xbfb8aa3b, v104
	v_mul_f32_e32 v119, 0xbfb8aa3b, v105
	v_exp_f32_e32 v118, v118
	v_exp_f32_e32 v119, v119
	v_rcp_f32_e32 v112, v112
	v_rcp_f32_e32 v113, v113
	v_add_f32_e32 v118, 1.0, v118
	v_add_f32_e32 v119, 1.0, v119
	v_rcp_f32_e32 v118, v118
	v_rcp_f32_e32 v119, v119
	v_mul_f32_e32 v102, v102, v112
	v_mul_f32_e32 v103, v103, v113
	v_mul_f32_e32 v108, v108, v110
	v_mul_f32_e32 v109, v109, v111
	v_mul_f32_e32 v102, v98, v102
	v_mul_f32_e32 v103, v99, v103
	v_mul_f32_e32 v98, v104, v118
	v_mul_f32_e32 v99, v105, v119
	s_nop 0
	v_mul_f32_e32 v104, v100, v98
	v_mul_f32_e32 v105, v101, v99
	v_cvt_pk_bf16_f32 v100, v102, v103
	v_mul_f32_e32 v102, 0xbfb8aa3b, v94
	v_mul_f32_e32 v103, 0xbfb8aa3b, v95
	v_exp_f32_e32 v102, v102
	v_exp_f32_e32 v103, v103
	v_cvt_pk_bf16_f32 v101, v104, v105
	v_or_b32_e32 v104, 16, v0
	v_mad_i64_i32 v[104:105], s[0:1], v104, s2, v[114:115]
	v_cvt_pk_bf16_f32 v98, v106, v107
	v_cvt_pk_bf16_f32 v99, v108, v109
	v_add_f32_e32 v102, 1.0, v102
	v_add_f32_e32 v103, 1.0, v103
	v_lshl_add_u64 v[104:105], v[104:105], 0, v[116:117]
	v_rcp_f32_e32 v102, v102
	v_rcp_f32_e32 v103, v103
	global_store_dwordx4 v[104:105], v[98:101], off
	v_mul_f32_e32 v94, v94, v102
	v_mul_f32_e32 v95, v95, v103
	s_nop 0
	v_mul_f32_e32 v98, 0xbfb8aa3b, v96
	v_mul_f32_e32 v99, 0xbfb8aa3b, v97
	v_exp_f32_e32 v98, v98
	v_exp_f32_e32 v99, v99
	v_mul_f32_e32 v90, v90, v94
	v_mul_f32_e32 v91, v91, v95
	v_add_f32_e32 v94, 1.0, v98
	v_add_f32_e32 v95, 1.0, v99
	v_mul_f32_e32 v98, 0xbfb8aa3b, v86
	v_mul_f32_e32 v99, 0xbfb8aa3b, v87
	v_rcp_f32_e32 v94, v94
	v_rcp_f32_e32 v95, v95
	v_exp_f32_e32 v98, v98
	v_exp_f32_e32 v99, v99
	v_mul_f32_e32 v94, v96, v94
	v_mul_f32_e32 v95, v97, v95
	v_add_f32_e32 v96, 1.0, v98
	v_add_f32_e32 v97, 1.0, v99
	v_mul_f32_e32 v98, 0xbfb8aa3b, v88
	v_mul_f32_e32 v99, 0xbfb8aa3b, v89
	v_exp_f32_e32 v98, v98
	v_exp_f32_e32 v99, v99
	v_rcp_f32_e32 v96, v96
	v_rcp_f32_e32 v97, v97
	v_add_f32_e32 v98, 1.0, v98
	v_add_f32_e32 v99, 1.0, v99
	v_rcp_f32_e32 v98, v98
	v_rcp_f32_e32 v99, v99
	v_mul_f32_e32 v86, v86, v96
	v_mul_f32_e32 v87, v87, v97
	v_mul_f32_e32 v92, v92, v94
	v_mul_f32_e32 v93, v93, v95
	v_mul_f32_e32 v86, v82, v86
	v_mul_f32_e32 v87, v83, v87
	v_mul_f32_e32 v82, v88, v98
	v_mul_f32_e32 v83, v89, v99
	s_nop 0
	v_mul_f32_e32 v88, v84, v82
	v_mul_f32_e32 v89, v85, v83
	v_cvt_pk_bf16_f32 v84, v86, v87
	v_mul_f32_e32 v86, 0xbfb8aa3b, v78
	v_mul_f32_e32 v87, 0xbfb8aa3b, v79
	v_exp_f32_e32 v86, v86
	v_exp_f32_e32 v87, v87
	v_cvt_pk_bf16_f32 v85, v88, v89
	v_or_b32_e32 v88, 32, v0
	v_mad_i64_i32 v[88:89], s[0:1], v88, s2, v[114:115]
;   DI void operator()(const f32x4 (&acc)[2][2][4][2], const Unit& u, int wr, int wc, int fr, int fq) const {
;     asm volatile("" ::: "memory");
;     const int row0 = u.pm * BM + wr * 64 + fr, col0 = u.pn * HALF + wc * 32 + 8 * fq;
; #pragma unroll
;     for (int ai = 0; ai < 2; ++ai)
; #pragma unroll
;       for (int m = 0; m < 4; ++m) {
;         float a[8];
; #pragma unroll
;         for (int n = 0; n < 2; ++n)
; #pragma unroll
;           for (int e = 0; e < 4; ++e) {
;             float gte = acc[ai][0][m][n][e], up = acc[ai][1][m][n][e];
;             a[n * 4 + e] = gte * __builtin_amdgcn_rcpf(1.f + __builtin_amdgcn_exp2f(-gte * LOG2E)) * up;
;           }
;         *(uint4*)(act + (size_t)(row0 + ai * HALF + m * 16) * FFN + col0) =
;             make_uint4(pack_bf16(a[0], a[1]), pack_bf16(a[2], a[3]), pack_bf16(a[4], a[5]), pack_bf16(a[6], a[7]));
;       }
	v_cvt_pk_bf16_f32 v82, v90, v91
	v_cvt_pk_bf16_f32 v83, v92, v93
	v_add_f32_e32 v86, 1.0, v86
	v_add_f32_e32 v87, 1.0, v87
	v_lshl_add_u64 v[88:89], v[88:89], 0, v[116:117]
	v_rcp_f32_e32 v86, v86
	v_rcp_f32_e32 v87, v87
	global_store_dwordx4 v[88:89], v[82:85], off
	v_mul_f32_e32 v78, v78, v86
	v_mul_f32_e32 v79, v79, v87
	s_nop 0
	v_mul_f32_e32 v82, 0xbfb8aa3b, v80
	v_mul_f32_e32 v83, 0xbfb8aa3b, v81
	v_exp_f32_e32 v82, v82
	v_exp_f32_e32 v83, v83
	v_mul_f32_e32 v74, v74, v78
	v_mul_f32_e32 v75, v75, v79
	v_add_f32_e32 v78, 1.0, v82
	v_add_f32_e32 v79, 1.0, v83
	v_mul_f32_e32 v82, 0xbfb8aa3b, v70
	v_mul_f32_e32 v83, 0xbfb8aa3b, v71
	v_rcp_f32_e32 v78, v78
	v_rcp_f32_e32 v79, v79
	v_exp_f32_e32 v82, v82
	v_exp_f32_e32 v83, v83
	v_mul_f32_e32 v78, v80, v78
	v_mul_f32_e32 v79, v81, v79
	v_add_f32_e32 v80, 1.0, v82
	v_add_f32_e32 v81, 1.0, v83
	v_mul_f32_e32 v82, 0xbfb8aa3b, v72
	v_mul_f32_e32 v83, 0xbfb8aa3b, v73
	v_exp_f32_e32 v82, v82
	v_exp_f32_e32 v83, v83
	v_rcp_f32_e32 v80, v80
	v_rcp_f32_e32 v81, v81
	v_add_f32_e32 v82, 1.0, v82
	v_add_f32_e32 v83, 1.0, v83
	v_rcp_f32_e32 v82, v82
	v_rcp_f32_e32 v83, v83
	v_mul_f32_e32 v70, v70, v80
	v_mul_f32_e32 v71, v71, v81
	v_mul_f32_e32 v76, v76, v78
	v_mul_f32_e32 v77, v77, v79
	v_mul_f32_e32 v70, v66, v70
	v_mul_f32_e32 v71, v67, v71
	v_mul_f32_e32 v66, v72, v82
	v_mul_f32_e32 v67, v73, v83
	s_nop 0
	v_mul_f32_e32 v72, v68, v66
	v_mul_f32_e32 v73, v69, v67
	v_cvt_pk_bf16_f32 v68, v70, v71
	v_mul_f32_e32 v71, 0xbfb8aa3b, v62
	v_cvt_pk_bf16_f32 v69, v72, v73
	v_exp_f32_e32 v72, v71
	v_mul_f32_e32 v71, 0xbfb8aa3b, v63
	v_exp_f32_e32 v73, v71
	v_or_b32_e32 v70, 48, v0
	v_mad_i64_i32 v[70:71], s[0:1], v70, s2, v[114:115]
	v_cvt_pk_bf16_f32 v66, v74, v75
	v_cvt_pk_bf16_f32 v67, v76, v77
	v_add_f32_e32 v72, 1.0, v72
	v_add_f32_e32 v73, 1.0, v73
	v_lshl_add_u64 v[70:71], v[70:71], 0, v[116:117]
	v_rcp_f32_e32 v72, v72
	v_rcp_f32_e32 v73, v73
	global_store_dwordx4 v[70:71], v[66:69], off
	v_mul_f32_e32 v62, v62, v72
	v_mul_f32_e32 v63, v63, v73
	s_nop 0
	v_mul_f32_e32 v66, 0xbfb8aa3b, v64
	v_mul_f32_e32 v67, 0xbfb8aa3b, v65
	v_exp_f32_e32 v66, v66
	v_exp_f32_e32 v67, v67
	v_mul_f32_e32 v58, v58, v62
	v_mul_f32_e32 v59, v59, v63
	v_add_u32_e32 v68, 0x80, v0
	v_add_f32_e32 v62, 1.0, v66
	v_add_f32_e32 v63, 1.0, v67
	v_mul_f32_e32 v66, 0xbfb8aa3b, v54
	v_mul_f32_e32 v67, 0xbfb8aa3b, v55
	v_rcp_f32_e32 v62, v62
	v_rcp_f32_e32 v63, v63
	v_exp_f32_e32 v66, v66
	v_exp_f32_e32 v67, v67
	v_mul_f32_e32 v62, v64, v62
	v_mul_f32_e32 v63, v65, v63
	v_add_f32_e32 v64, 1.0, v66
	v_add_f32_e32 v65, 1.0, v67
	v_mul_f32_e32 v66, 0xbfb8aa3b, v56
	v_mul_f32_e32 v67, 0xbfb8aa3b, v57
	v_exp_f32_e32 v66, v66
	v_exp_f32_e32 v67, v67
	v_rcp_f32_e32 v64, v64
	v_rcp_f32_e32 v65, v65
	v_add_f32_e32 v66, 1.0, v66
	v_add_f32_e32 v67, 1.0, v67
	v_rcp_f32_e32 v66, v66
	v_rcp_f32_e32 v67, v67
	v_mul_f32_e32 v54, v54, v64
	v_mul_f32_e32 v55, v55, v65
	v_mul_f32_e32 v60, v60, v62
	v_mul_f32_e32 v61, v61, v63
	v_mul_f32_e32 v54, v50, v54
	v_mul_f32_e32 v55, v51, v55
	v_mul_f32_e32 v50, v56, v66
	v_mul_f32_e32 v51, v57, v67
	s_nop 0
	v_mul_f32_e32 v56, v52, v50
	v_mul_f32_e32 v57, v53, v51
	v_mul_f32_e32 v53, 0xbfb8aa3b, v46
	v_cvt_pk_bf16_f32 v52, v54, v55
	v_exp_f32_e32 v54, v53
	v_mul_f32_e32 v53, 0xbfb8aa3b, v47
	v_exp_f32_e32 v55, v53
	v_cvt_pk_bf16_f32 v53, v56, v57
	v_mad_i64_i32 v[56:57], s[0:1], v68, s2, v[114:115]
	v_cvt_pk_bf16_f32 v50, v58, v59
	v_cvt_pk_bf16_f32 v51, v60, v61
	v_add_f32_e32 v54, 1.0, v54
	v_add_f32_e32 v55, 1.0, v55
	v_lshl_add_u64 v[56:57], v[56:57], 0, v[116:117]
	v_rcp_f32_e32 v54, v54
	v_rcp_f32_e32 v55, v55
	global_store_dwordx4 v[56:57], v[50:53], off
	v_mul_f32_e32 v46, v46, v54
	v_mul_f32_e32 v47, v47, v55
	s_nop 0
	v_mul_f32_e32 v50, 0xbfb8aa3b, v48
	v_mul_f32_e32 v51, 0xbfb8aa3b, v49
	v_exp_f32_e32 v50, v50
	v_exp_f32_e32 v51, v51
	v_mul_f32_e32 v42, v42, v46
	v_mul_f32_e32 v43, v43, v47
	v_add_f32_e32 v46, 1.0, v50
	v_add_f32_e32 v47, 1.0, v51
	v_mul_f32_e32 v50, 0xbfb8aa3b, v38
	v_mul_f32_e32 v51, 0xbfb8aa3b, v39
	v_rcp_f32_e32 v46, v46
	v_rcp_f32_e32 v47, v47
	v_exp_f32_e32 v50, v50
	v_exp_f32_e32 v51, v51
	v_mul_f32_e32 v46, v48, v46
	v_mul_f32_e32 v47, v49, v47
	v_add_f32_e32 v48, 1.0, v50
	v_add_f32_e32 v49, 1.0, v51
; #define PG8_WAIT_V(n) asm volatile("s_waitcnt vmcnt(" #n ")" ::: "memory")
; #define PG8_BAR __builtin_amdgcn_s_barrier()
; template <class Epi, class Sched>
; DI void gemm_phase(LAS unsigned char* lds, const Gemm g, const Sched& S, const Epi& E) {
;     ...
;   PG8_WAIT_V(0);
;   if (wr == 0) PG8_BAR;
;   PG8_BAR;
;   DI void operator()(const f32x4 (&acc)[2][2][4][2], const Unit& u, int wr, int wc, int fr, int fq) const {
;     asm volatile("" ::: "memory");
;     const int row0 = u.pm * BM + wr * 64 + fr, col0 = u.pn * HALF + wc * 32 + 8 * fq;
; #pragma unroll
;     for (int ai = 0; ai < 2; ++ai)
; #pragma unroll
;       for (int m = 0; m < 4; ++m) {
;         float a[8];
; #pragma unroll
;         for (int n = 0; n < 2; ++n)
; #pragma unroll
;           for (int e = 0; e < 4; ++e) {
;             float gte = acc[ai][0][m][n][e], up = acc[ai][1][m][n][e];
;             a[n * 4 + e] = gte * __builtin_amdgcn_rcpf(1.f + __builtin_amdgcn_exp2f(-gte * LOG2E)) * up;
;           }
;         *(uint4*)(act + (size_t)(row0 + ai * HALF + m * 16) * FFN + col0) =
;             make_uint4(pack_bf16(a[0], a[1]), pack_bf16(a[2], a[3]), pack_bf16(a[4], a[5]), pack_bf16(a[6], a[7]));
;       }
	v_mul_f32_e32 v50, 0xbfb8aa3b, v40
	v_mul_f32_e32 v51, 0xbfb8aa3b, v41
	v_exp_f32_e32 v50, v50
	v_exp_f32_e32 v51, v51
	v_rcp_f32_e32 v48, v48
	v_rcp_f32_e32 v49, v49
	v_add_f32_e32 v50, 1.0, v50
	v_add_f32_e32 v51, 1.0, v51
	v_rcp_f32_e32 v50, v50
	v_rcp_f32_e32 v51, v51
	v_mul_f32_e32 v38, v38, v48
	v_mul_f32_e32 v39, v39, v49
	v_mul_f32_e32 v44, v44, v46
	v_mul_f32_e32 v45, v45, v47
	v_mul_f32_e32 v38, v34, v38
	v_mul_f32_e32 v39, v35, v39
	v_mul_f32_e32 v34, v40, v50
	v_mul_f32_e32 v35, v41, v51
	s_nop 0
	v_mul_f32_e32 v40, v36, v34
	v_mul_f32_e32 v41, v37, v35
	v_cvt_pk_bf16_f32 v36, v38, v39
	v_mul_f32_e32 v38, 0xbfb8aa3b, v30
	v_mul_f32_e32 v39, 0xbfb8aa3b, v31
	v_exp_f32_e32 v38, v38
	v_exp_f32_e32 v39, v39
	v_cvt_pk_bf16_f32 v37, v40, v41
	v_add_u32_e32 v40, 0x90, v0
	v_mad_i64_i32 v[40:41], s[0:1], v40, s2, v[114:115]
	v_cvt_pk_bf16_f32 v34, v42, v43
	v_cvt_pk_bf16_f32 v35, v44, v45
	v_add_f32_e32 v38, 1.0, v38
	v_add_f32_e32 v39, 1.0, v39
	v_lshl_add_u64 v[40:41], v[40:41], 0, v[116:117]
	v_rcp_f32_e32 v38, v38
	v_rcp_f32_e32 v39, v39
	global_store_dwordx4 v[40:41], v[34:37], off
	v_mul_f32_e32 v30, v30, v38
	v_mul_f32_e32 v31, v31, v39
	s_nop 0
	v_mul_f32_e32 v34, 0xbfb8aa3b, v32
	v_mul_f32_e32 v35, 0xbfb8aa3b, v33
	v_exp_f32_e32 v34, v34
	v_exp_f32_e32 v35, v35
	v_mul_f32_e32 v26, v26, v30
	v_mul_f32_e32 v27, v27, v31
	v_add_f32_e32 v30, 1.0, v34
	v_add_f32_e32 v31, 1.0, v35
	v_mul_f32_e32 v34, 0xbfb8aa3b, v22
	v_mul_f32_e32 v35, 0xbfb8aa3b, v23
	v_rcp_f32_e32 v30, v30
	v_rcp_f32_e32 v31, v31
	v_exp_f32_e32 v34, v34
	v_exp_f32_e32 v35, v35
	v_mul_f32_e32 v30, v32, v30
	v_mul_f32_e32 v31, v33, v31
	v_add_f32_e32 v32, 1.0, v34
	v_add_f32_e32 v33, 1.0, v35
	v_mul_f32_e32 v34, 0xbfb8aa3b, v24
	v_mul_f32_e32 v35, 0xbfb8aa3b, v25
	v_exp_f32_e32 v34, v34
	v_exp_f32_e32 v35, v35
	v_rcp_f32_e32 v32, v32
	v_rcp_f32_e32 v33, v33
	v_add_f32_e32 v34, 1.0, v34
	v_add_f32_e32 v35, 1.0, v35
	v_rcp_f32_e32 v34, v34
	v_rcp_f32_e32 v35, v35
	v_mul_f32_e32 v22, v22, v32
	v_mul_f32_e32 v23, v23, v33
	v_mul_f32_e32 v28, v28, v30
	v_mul_f32_e32 v29, v29, v31
	v_mul_f32_e32 v22, v18, v22
	v_mul_f32_e32 v23, v19, v23
	v_mul_f32_e32 v18, v24, v34
	v_mul_f32_e32 v19, v25, v35
	s_nop 0
	v_mul_f32_e32 v24, v20, v18
	v_mul_f32_e32 v25, v21, v19
	v_cvt_pk_bf16_f32 v20, v22, v23
	v_mul_f32_e32 v22, 0xbfb8aa3b, v14
	v_mul_f32_e32 v23, 0xbfb8aa3b, v15
	v_exp_f32_e32 v22, v22
	v_exp_f32_e32 v23, v23
	v_cvt_pk_bf16_f32 v21, v24, v25
	v_add_u32_e32 v24, 0xa0, v0
	v_mad_i64_i32 v[24:25], s[0:1], v24, s2, v[114:115]
	v_cvt_pk_bf16_f32 v18, v26, v27
	v_cvt_pk_bf16_f32 v19, v28, v29
	v_add_f32_e32 v22, 1.0, v22
	v_add_f32_e32 v23, 1.0, v23
	v_lshl_add_u64 v[24:25], v[24:25], 0, v[116:117]
	v_rcp_f32_e32 v22, v22
	v_rcp_f32_e32 v23, v23
	global_store_dwordx4 v[24:25], v[18:21], off
	v_add_u32_e32 v0, 0xb0, v0
	v_mul_f32_e32 v14, v14, v22
	v_mul_f32_e32 v15, v15, v23
	v_mul_f32_e32 v18, 0xbfb8aa3b, v16
	v_mul_f32_e32 v19, 0xbfb8aa3b, v17
	v_exp_f32_e32 v18, v18
	v_exp_f32_e32 v19, v19
	v_mul_f32_e32 v10, v10, v14
	v_mul_f32_e32 v11, v11, v15
	v_add_f32_e32 v14, 1.0, v18
	v_add_f32_e32 v15, 1.0, v19
	v_mul_f32_e32 v18, 0xbfb8aa3b, v6
	v_mul_f32_e32 v19, 0xbfb8aa3b, v7
	v_rcp_f32_e32 v14, v14
	v_rcp_f32_e32 v15, v15
	v_exp_f32_e32 v18, v18
	v_exp_f32_e32 v19, v19
	v_mul_f32_e32 v14, v16, v14
	v_mul_f32_e32 v15, v17, v15
	v_add_f32_e32 v16, 1.0, v18
	v_add_f32_e32 v17, 1.0, v19
	v_mul_f32_e32 v18, 0xbfb8aa3b, v8
	v_mul_f32_e32 v19, 0xbfb8aa3b, v9
	v_exp_f32_e32 v18, v18
	v_exp_f32_e32 v19, v19
	v_rcp_f32_e32 v16, v16
	v_rcp_f32_e32 v17, v17
	v_add_f32_e32 v18, 1.0, v18
	v_add_f32_e32 v19, 1.0, v19
	v_rcp_f32_e32 v18, v18
	v_rcp_f32_e32 v19, v19
	v_mul_f32_e32 v6, v6, v16
	v_mul_f32_e32 v7, v7, v17
	v_mul_f32_e32 v12, v12, v14
	v_mul_f32_e32 v13, v13, v15
	v_mul_f32_e32 v6, v2, v6
	v_mul_f32_e32 v7, v3, v7
	v_mul_f32_e32 v2, v8, v18
	v_mul_f32_e32 v3, v9, v19
	s_nop 0
	v_mul_f32_e32 v8, v4, v2
	v_mul_f32_e32 v9, v5, v3
	v_cvt_pk_bf16_f32 v4, v6, v7
	v_mad_i64_i32 v[6:7], s[0:1], v0, s2, v[114:115]
	v_cvt_pk_bf16_f32 v2, v10, v11
	v_cvt_pk_bf16_f32 v3, v12, v13
	v_cvt_pk_bf16_f32 v5, v8, v9
	v_lshl_add_u64 v[6:7], v[6:7], 0, v[116:117]
	global_store_dwordx4 v[6:7], v[2:5], off
	s_waitcnt vmcnt(0)
	s_cbranch_scc0 .LBB0_194
	s_barrier
